# q_tile: the RoPE cos/sin rows of all 8 epilogue iterations are touched once before the C tile is staged (discarded loads) so the compiled per-iteration loads hit L1
# speedup vs baseline: 1.0053x; 1.0053x over previous
; DI int tidx() { int t = threadIdx.x & 255; asm volatile("" : "+v"(t)); return t; }
; #define GM_LOAD(RA, RB, KT)                                                                 \
;   _Pragma("unroll") for (int i = 0; i < 4; ++i) {                                           \
;     RA[i] = *(const u32x4*)(ag + (size_t)(32 * i) * lda + (KT) * 64);                       \
;     RB[i] = *(const u32x4*)(bg + (size_t)(32 * i) * ldb + (KT) * 64);                       \
;   }
; template <bool DEEP = true>
; DI void gemm_main(f32x4 (&acc)[4][4], const u16* __restrict__ A, int lda, const u16* __restrict__ B, int ldb, int K, u16* lds) {
;   const int tid = tidx(), lane = tid & 63, w = tid >> 6;
;   const int wm = w >> 1, wn = w & 1, fr = lane & 15, fq = lane >> 4;
;   const int lrow = tid >> 3, lch = (tid & 7) * 8, lsw = ((tid & 7) ^ (lrow & 7)) * 8;
;   const u16* ag = A + (size_t)lrow * lda + lch;
;   const u16* bg = B + (size_t)lrow * ldb + lch;
;   const int nk = K >> 6;
;   if (DEEP) {
;     u32x4 ra0[4], rb0[4], ra1[4], rb1[4];
;     GM_LOAD(ra0, rb0, 0)
;     GM_LOAD(ra1, rb1, 1)
;     __syncthreads();
;     GM_STORE(ra0, rb0, 0)
;     __syncthreads();
;     for (int kt = 0; kt < nk; kt += 2) {
;       if (kt + 2 < nk) { GM_LOAD(ra0, rb0, kt + 2) }
;       GM_COMPUTE(0)
.LBB0_348:
	s_or_b64 exec, exec, s[8:9]
	s_mul_i32 s19, s19, 3
	s_sub_i32 s0, s20, s19
	s_lshl_b32 s8, s0, 7
	s_mul_i32 s0, s18, 0x1540
	s_mul_hi_i32 s1, s18, 0x1540
	s_add_u32 s0, s10, s0
	s_addc_u32 s1, s11, s1
	s_ashr_i32 s9, s8, 31
	v_mov_b32_e32 v83, v169
	s_lshl_b64 s[16:17], s[8:9], 9
	v_mov_b64_e32 v[2:3], s[0:1]
	v_ashrrev_i32_e32 v34, 3, v83
	v_lshlrev_b32_e32 v0, 4, v83
	s_add_u32 s16, s21, s16
	v_ashrrev_i32_e32 v35, 31, v34
	v_mad_i64_i32 v[2:3], s[0:1], v34, s60, v[2:3]
	v_and_b32_e32 v0, 0x70, v0
	s_addc_u32 s17, s22, s17
	v_lshl_add_u64 v[66:67], v[2:3], 0, v[0:1]
	v_lshlrev_b64 v[2:3], 9, v[34:35]
	s_mov_b32 s0, 0x2a000
	v_lshl_add_u64 v[2:3], s[16:17], 0, v[2:3]
	v_add_co_u32_e32 v70, vcc, s0, v66
	v_lshl_add_u64 v[68:69], v[2:3], 0, v[0:1]
	s_nop 0
	v_addc_co_u32_e32 v71, vcc, 0, v67, vcc
	s_movk_i32 s0, 0x4000
	v_add_co_u32_e32 v72, vcc, s0, v68
	s_mov_b32 s0, 0x8000
	s_nop 0
	v_addc_co_u32_e32 v73, vcc, 0, v69, vcc
	v_add_co_u32_e32 v74, vcc, s28, v66
	global_load_dwordx4 v[2:5], v[66:67], off offset:1536
	global_load_dwordx4 v[6:9], v[68:69], off
	v_addc_co_u32_e32 v75, vcc, 0, v67, vcc
	v_add_co_u32_e32 v76, vcc, s0, v68
	s_mov_b32 s0, 0x7f000
	s_nop 0
	v_addc_co_u32_e32 v77, vcc, 0, v69, vcc
	global_load_dwordx4 v[10:13], v[70:71], off offset:3584
	v_add_co_u32_e32 v78, vcc, s0, v66
	global_load_dwordx4 v[18:21], v[74:75], off offset:1536
	s_nop 0
	v_addc_co_u32_e32 v79, vcc, 0, v67, vcc
	global_load_dwordx4 v[26:29], v[78:79], off offset:3584
	s_mov_b32 s0, 0xc000
	global_load_dwordx4 v[14:17], v[72:73], off
	v_add_co_u32_e32 v80, vcc, s0, v68
	global_load_dwordx4 v[22:25], v[76:77], off
	s_nop 0
	v_addc_co_u32_e32 v81, vcc, 0, v69, vcc
	global_load_dwordx4 v[30:33], v[80:81], off
	v_xor_b32_e32 v0, v34, v83
	v_lshlrev_b32_e32 v0, 4, v0
	v_lshlrev_b32_e32 v34, 7, v34
	v_and_b32_e32 v0, 0x70, v0
	v_add3_u32 v85, s33, v0, v34
	global_load_dwordx4 v[46:49], v[66:67], off offset:1664
	global_load_dwordx4 v[42:45], v[70:71], off offset:3712
	global_load_dwordx4 v[38:41], v[74:75], off offset:1664
	global_load_dwordx4 v[34:37], v[78:79], off offset:3712
	global_load_dwordx4 v[62:65], v[68:69], off offset:128
	global_load_dwordx4 v[58:61], v[72:73], off offset:128
	global_load_dwordx4 v[54:57], v[76:77], off offset:128
	global_load_dwordx4 v[50:53], v[80:81], off offset:128
	s_waitcnt lgkmcnt(0)
	s_barrier
	v_and_b32_e32 v84, 15, v83
	v_lshrrev_b32_e32 v86, 1, v83
	s_mov_b32 s0, 0x1ffffc0
	v_and_or_b32 v84, v86, s0, v84
	v_lshrrev_b32_e32 v0, 4, v83
	v_bfe_u32 v87, v83, 4, 2
	v_lshl_add_u32 v88, v84, 7, s33
	v_lshlrev_b32_e32 v84, 7, v83
	v_and_b32_e32 v83, 7, v83
	v_and_b32_e32 v84, 0x2780, v84
	v_bitop3_b32 v0, v0, v83, 3 bitop3:0x6c
	v_add_u32_e32 v89, s33, v84
	v_lshlrev_b32_e32 v0, 4, v0
	v_add_u32_e32 v86, v88, v0
	v_add_u32_e32 v84, v89, v0
	v_bitop3_b32 v0, v87, v83, 4 bitop3:0x36
	v_lshlrev_b32_e32 v0, 4, v0
	v_add_u32_e32 v83, v88, v0
	v_add_u32_e32 v0, v89, v0
	s_waitcnt vmcnt(15)
	ds_write_b128 v85, v[2:5]
	s_waitcnt vmcnt(13)
	ds_write_b128 v85, v[10:13] offset:4096
	s_waitcnt vmcnt(12)
	ds_write_b128 v85, v[18:21] offset:8192
	s_waitcnt vmcnt(11)
	ds_write_b128 v85, v[26:29] offset:12288
	ds_write_b128 v85, v[6:9] offset:16384
	s_waitcnt vmcnt(10)
	ds_write_b128 v85, v[14:17] offset:20480
	s_waitcnt vmcnt(9)
	ds_write_b128 v85, v[22:25] offset:24576
	s_waitcnt vmcnt(8)
	ds_write_b128 v85, v[30:33] offset:28672
	s_waitcnt lgkmcnt(0)
	s_barrier
	global_load_dwordx4 v[2:5], v[66:67], off offset:1792
	global_load_dwordx4 v[6:9], v[68:69], off offset:256
	global_load_dwordx4 v[10:13], v[70:71], off offset:3840
	global_load_dwordx4 v[14:17], v[72:73], off offset:256
	global_load_dwordx4 v[18:21], v[74:75], off offset:1792
	global_load_dwordx4 v[22:25], v[76:77], off offset:256
	global_load_dwordx4 v[26:29], v[78:79], off offset:3840
	global_load_dwordx4 v[30:33], v[80:81], off offset:256
	s_setprio 1
	ds_read_b128 v[88:91], v86
	ds_read_b128 v[92:95], v86 offset:2048
	ds_read_b128 v[96:99], v86 offset:4096
	ds_read_b128 v[100:103], v86 offset:6144
	ds_read_b128 v[104:107], v84 offset:16384
	ds_read_b128 v[120:123], v84 offset:18432
	ds_read_b128 v[136:139], v84 offset:20480
	ds_read_b128 v[152:155], v84 offset:22528
	s_waitcnt lgkmcnt(3)
	v_mfma_f32_16x16x32_bf16 v[108:111], v[88:91], v[104:107], 0
	v_mfma_f32_16x16x32_bf16 v[112:115], v[92:95], v[104:107], 0
	v_mfma_f32_16x16x32_bf16 v[116:119], v[96:99], v[104:107], 0
	v_mfma_f32_16x16x32_bf16 v[104:107], v[100:103], v[104:107], 0
	s_waitcnt lgkmcnt(2)
	v_mfma_f32_16x16x32_bf16 v[124:127], v[88:91], v[120:123], 0
	v_mfma_f32_16x16x32_bf16 v[128:131], v[92:95], v[120:123], 0
	v_mfma_f32_16x16x32_bf16 v[132:135], v[96:99], v[120:123], 0
	v_mfma_f32_16x16x32_bf16 v[120:123], v[100:103], v[120:123], 0
	s_waitcnt lgkmcnt(1)
	v_mfma_f32_16x16x32_bf16 v[140:143], v[88:91], v[136:139], 0
	v_mfma_f32_16x16x32_bf16 v[144:147], v[92:95], v[136:139], 0
	v_mfma_f32_16x16x32_bf16 v[148:151], v[96:99], v[136:139], 0
	v_mfma_f32_16x16x32_bf16 v[136:139], v[100:103], v[136:139], 0
	s_waitcnt lgkmcnt(0)
	v_mfma_f32_16x16x32_bf16 v[88:91], v[88:91], v[152:155], 0
	v_mfma_f32_16x16x32_bf16 v[92:95], v[92:95], v[152:155], 0
	v_mfma_f32_16x16x32_bf16 v[96:99], v[96:99], v[152:155], 0
	v_mfma_f32_16x16x32_bf16 v[100:103], v[100:103], v[152:155], 0
	ds_read_b128 v[152:155], v83
	ds_read_b128 v[156:159], v83 offset:2048
	ds_read_b128 v[164:167], v83 offset:4096
	ds_read_b128 v[182:185], v83 offset:6144
	ds_read_b128 v[186:189], v0 offset:16384
	s_waitcnt lgkmcnt(0)
; #define GM_LOAD(RA, RB, KT)                                                                 \
;   _Pragma("unroll") for (int i = 0; i < 4; ++i) {                                           \
;     RA[i] = *(const u32x4*)(ag + (size_t)(32 * i) * lda + (KT) * 64);                       \
;     RB[i] = *(const u32x4*)(bg + (size_t)(32 * i) * ldb + (KT) * 64);                       \
;   }
; template <bool DEEP = true>
; DI void gemm_main(f32x4 (&acc)[4][4], const u16* __restrict__ A, int lda, const u16* __restrict__ B, int ldb, int K, u16* lds) {
;     ...
;     for (int kt = 0; kt < nk; kt += 2) {
;       if (kt + 2 < nk) { GM_LOAD(ra0, rb0, kt + 2) }
;       GM_COMPUTE(0)
;       __builtin_amdgcn_sched_barrier(0);
;       GM_STORE(ra1, rb1, 1)
;       __syncthreads();
;       if (kt + 3 < nk) { GM_LOAD(ra1, rb1, kt + 3) }
;       GM_COMPUTE(1)
;       __builtin_amdgcn_sched_barrier(0);
;       if (kt + 2 < nk) { GM_STORE(ra0, rb0, 0) }
	v_mfma_f32_16x16x32_bf16 v[108:111], v[152:155], v[186:189], v[108:111]
	v_mfma_f32_16x16x32_bf16 v[112:115], v[156:159], v[186:189], v[112:115]
	v_mfma_f32_16x16x32_bf16 v[116:119], v[164:167], v[186:189], v[116:119]
	v_mfma_f32_16x16x32_bf16 v[104:107], v[182:185], v[186:189], v[104:107]
	ds_read_b128 v[186:189], v0 offset:18432
	s_waitcnt lgkmcnt(0)
	v_mfma_f32_16x16x32_bf16 v[124:127], v[152:155], v[186:189], v[124:127]
	v_mfma_f32_16x16x32_bf16 v[128:131], v[156:159], v[186:189], v[128:131]
	v_mfma_f32_16x16x32_bf16 v[132:135], v[164:167], v[186:189], v[132:135]
	v_mfma_f32_16x16x32_bf16 v[120:123], v[182:185], v[186:189], v[120:123]
	ds_read_b128 v[186:189], v0 offset:20480
	s_waitcnt lgkmcnt(0)
	v_mfma_f32_16x16x32_bf16 v[140:143], v[152:155], v[186:189], v[140:143]
	v_mfma_f32_16x16x32_bf16 v[144:147], v[156:159], v[186:189], v[144:147]
	v_mfma_f32_16x16x32_bf16 v[148:151], v[164:167], v[186:189], v[148:151]
	v_mfma_f32_16x16x32_bf16 v[136:139], v[182:185], v[186:189], v[136:139]
	ds_read_b128 v[186:189], v0 offset:22528
	s_waitcnt lgkmcnt(0)
	v_mfma_f32_16x16x32_bf16 v[88:91], v[152:155], v[186:189], v[88:91]
	v_mfma_f32_16x16x32_bf16 v[92:95], v[156:159], v[186:189], v[92:95]
	v_mfma_f32_16x16x32_bf16 v[96:99], v[164:167], v[186:189], v[96:99]
	v_mfma_f32_16x16x32_bf16 v[100:103], v[182:185], v[186:189], v[100:103]
	s_setprio 0
	s_waitcnt vmcnt(15)
	ds_write_b128 v85, v[46:49] offset:32768
	s_waitcnt vmcnt(11)
	ds_write_b128 v85, v[62:65] offset:49152
	ds_write_b128 v85, v[42:45] offset:36864
	s_waitcnt vmcnt(10)
	ds_write_b128 v85, v[58:61] offset:53248
	ds_write_b128 v85, v[38:41] offset:40960
	s_waitcnt vmcnt(9)
	ds_write_b128 v85, v[54:57] offset:57344
	ds_write_b128 v85, v[34:37] offset:45056
	s_waitcnt vmcnt(8)
	ds_write_b128 v85, v[50:53] offset:61440
	s_waitcnt lgkmcnt(0)
	s_barrier
	global_load_dwordx4 v[34:37], v[66:67], off offset:1920
	global_load_dwordx4 v[38:41], v[68:69], off offset:384
	global_load_dwordx4 v[42:45], v[70:71], off offset:3968
	global_load_dwordx4 v[46:49], v[72:73], off offset:384
	global_load_dwordx4 v[50:53], v[74:75], off offset:1920
	global_load_dwordx4 v[54:57], v[76:77], off offset:384
	global_load_dwordx4 v[58:61], v[78:79], off offset:3968
	global_load_dwordx4 v[62:65], v[80:81], off offset:384
	s_setprio 1
	ds_read_b128 v[66:69], v86 offset:32768
	ds_read_b128 v[70:73], v86 offset:34816
	ds_read_b128 v[74:77], v86 offset:36864
	ds_read_b128 v[78:81], v86 offset:38912
	ds_read_b128 v[152:155], v84 offset:49152
	s_waitcnt lgkmcnt(0)
	v_mfma_f32_16x16x32_bf16 v[108:111], v[66:69], v[152:155], v[108:111]
	v_mfma_f32_16x16x32_bf16 v[112:115], v[70:73], v[152:155], v[112:115]
	v_mfma_f32_16x16x32_bf16 v[116:119], v[74:77], v[152:155], v[116:119]
	v_mfma_f32_16x16x32_bf16 v[104:107], v[78:81], v[152:155], v[104:107]
	ds_read_b128 v[152:155], v84 offset:51200
	s_waitcnt lgkmcnt(0)
	v_mfma_f32_16x16x32_bf16 v[124:127], v[66:69], v[152:155], v[124:127]
	v_mfma_f32_16x16x32_bf16 v[128:131], v[70:73], v[152:155], v[128:131]
	v_mfma_f32_16x16x32_bf16 v[132:135], v[74:77], v[152:155], v[132:135]
	v_mfma_f32_16x16x32_bf16 v[120:123], v[78:81], v[152:155], v[120:123]
	ds_read_b128 v[152:155], v84 offset:53248
	s_waitcnt lgkmcnt(0)
	v_mfma_f32_16x16x32_bf16 v[140:143], v[66:69], v[152:155], v[140:143]
	v_mfma_f32_16x16x32_bf16 v[144:147], v[70:73], v[152:155], v[144:147]
	v_mfma_f32_16x16x32_bf16 v[148:151], v[74:77], v[152:155], v[148:151]
	v_mfma_f32_16x16x32_bf16 v[136:139], v[78:81], v[152:155], v[136:139]
	ds_read_b128 v[152:155], v84 offset:55296
	s_waitcnt lgkmcnt(0)
	v_mfma_f32_16x16x32_bf16 v[66:69], v[66:69], v[152:155], v[88:91]
	v_mfma_f32_16x16x32_bf16 v[70:73], v[70:73], v[152:155], v[92:95]
	v_mfma_f32_16x16x32_bf16 v[74:77], v[74:77], v[152:155], v[96:99]
	v_mfma_f32_16x16x32_bf16 v[78:81], v[78:81], v[152:155], v[100:103]
	ds_read_b128 v[88:91], v83 offset:32768
	ds_read_b128 v[92:95], v83 offset:34816
	ds_read_b128 v[96:99], v83 offset:36864
	ds_read_b128 v[100:103], v83 offset:38912
	ds_read_b128 v[152:155], v0 offset:49152
	s_waitcnt lgkmcnt(0)
	v_mfma_f32_16x16x32_bf16 v[108:111], v[88:91], v[152:155], v[108:111]
	v_mfma_f32_16x16x32_bf16 v[112:115], v[92:95], v[152:155], v[112:115]
	v_mfma_f32_16x16x32_bf16 v[116:119], v[96:99], v[152:155], v[116:119]
	v_mfma_f32_16x16x32_bf16 v[104:107], v[100:103], v[152:155], v[104:107]
	ds_read_b128 v[152:155], v0 offset:51200
	s_waitcnt lgkmcnt(0)
	v_mfma_f32_16x16x32_bf16 v[124:127], v[88:91], v[152:155], v[124:127]
	v_mfma_f32_16x16x32_bf16 v[128:131], v[92:95], v[152:155], v[128:131]
	v_mfma_f32_16x16x32_bf16 v[132:135], v[96:99], v[152:155], v[132:135]
	v_mfma_f32_16x16x32_bf16 v[120:123], v[100:103], v[152:155], v[120:123]
	ds_read_b128 v[152:155], v0 offset:53248
	s_waitcnt lgkmcnt(0)
	v_mfma_f32_16x16x32_bf16 v[140:143], v[88:91], v[152:155], v[140:143]
	v_mfma_f32_16x16x32_bf16 v[144:147], v[92:95], v[152:155], v[144:147]
	v_mfma_f32_16x16x32_bf16 v[148:151], v[96:99], v[152:155], v[148:151]
	v_mfma_f32_16x16x32_bf16 v[136:139], v[100:103], v[152:155], v[136:139]
	ds_read_b128 v[152:155], v0 offset:55296
	s_waitcnt lgkmcnt(0)
	v_mfma_f32_16x16x32_bf16 v[66:69], v[88:91], v[152:155], v[66:69]
	v_mfma_f32_16x16x32_bf16 v[70:73], v[92:95], v[152:155], v[70:73]
	v_mfma_f32_16x16x32_bf16 v[74:77], v[96:99], v[152:155], v[74:77]
	v_mfma_f32_16x16x32_bf16 v[78:81], v[100:103], v[152:155], v[78:81]
	s_setprio 0
	s_waitcnt vmcnt(15)
	ds_write_b128 v85, v[2:5]
	s_waitcnt vmcnt(14)
	ds_write_b128 v85, v[6:9] offset:16384
	s_waitcnt vmcnt(13)
	ds_write_b128 v85, v[10:13] offset:4096
	s_waitcnt vmcnt(12)
	ds_write_b128 v85, v[14:17] offset:20480
	s_waitcnt vmcnt(11)
	ds_write_b128 v85, v[18:21] offset:8192
	s_waitcnt vmcnt(10)
	ds_write_b128 v85, v[22:25] offset:24576
	s_waitcnt vmcnt(9)
	ds_write_b128 v85, v[26:29] offset:12288
	s_waitcnt vmcnt(8)
	ds_write_b128 v85, v[30:33] offset:28672
	s_waitcnt lgkmcnt(0)
	s_barrier
; #define GM_LOAD(RA, RB, KT)                                                                 \
;   _Pragma("unroll") for (int i = 0; i < 4; ++i) {                                           \
;     RA[i] = *(const u32x4*)(ag + (size_t)(32 * i) * lda + (KT) * 64);                       \
;     RB[i] = *(const u32x4*)(bg + (size_t)(32 * i) * ldb + (KT) * 64);                       \
;   }
; template <bool DEEP = true>
; DI void gemm_main(f32x4 (&acc)[4][4], const u16* __restrict__ A, int lda, const u16* __restrict__ B, int ldb, int K, u16* lds) {
;     ...
;     for (int kt = 0; kt < nk; kt += 2) {
;       if (kt + 2 < nk) { GM_LOAD(ra0, rb0, kt + 2) }
;       GM_COMPUTE(0)
;       __builtin_amdgcn_sched_barrier(0);
;       GM_STORE(ra1, rb1, 1)
;       __syncthreads();
;       if (kt + 3 < nk) { GM_LOAD(ra1, rb1, kt + 3) }
;       GM_COMPUTE(1)
;       __builtin_amdgcn_sched_barrier(0);
;       if (kt + 2 < nk) { GM_STORE(ra0, rb0, 0) }
;       __syncthreads();
;     }
	s_setprio 1
	ds_read_b128 v[2:5], v86
	ds_read_b128 v[6:9], v86 offset:2048
	ds_read_b128 v[10:13], v86 offset:4096
	ds_read_b128 v[14:17], v86 offset:6144
	ds_read_b128 v[18:21], v84 offset:16384
	ds_read_b128 v[88:91], v84 offset:18432
	s_waitcnt lgkmcnt(1)
	v_mfma_f32_16x16x32_bf16 v[22:25], v[2:5], v[18:21], v[108:111]
	v_mfma_f32_16x16x32_bf16 v[26:29], v[6:9], v[18:21], v[112:115]
	v_mfma_f32_16x16x32_bf16 v[30:33], v[10:13], v[18:21], v[116:119]
	v_mfma_f32_16x16x32_bf16 v[18:21], v[14:17], v[18:21], v[104:107]
	s_nop 2
	ds_read_b128 v[104:107], v84 offset:20480
	s_waitcnt lgkmcnt(1)
	v_mfma_f32_16x16x32_bf16 v[92:95], v[2:5], v[88:91], v[124:127]
	v_mfma_f32_16x16x32_bf16 v[96:99], v[6:9], v[88:91], v[128:131]
	v_mfma_f32_16x16x32_bf16 v[100:103], v[10:13], v[88:91], v[132:135]
	v_mfma_f32_16x16x32_bf16 v[88:91], v[14:17], v[88:91], v[120:123]
	s_nop 2
	ds_read_b128 v[120:123], v84 offset:22528
	s_waitcnt lgkmcnt(1)
	v_mfma_f32_16x16x32_bf16 v[108:111], v[2:5], v[104:107], v[140:143]
	v_mfma_f32_16x16x32_bf16 v[112:115], v[6:9], v[104:107], v[144:147]
	v_mfma_f32_16x16x32_bf16 v[116:119], v[10:13], v[104:107], v[148:151]
	v_mfma_f32_16x16x32_bf16 v[104:107], v[14:17], v[104:107], v[136:139]
	s_waitcnt lgkmcnt(0)
	v_mfma_f32_16x16x32_bf16 v[2:5], v[2:5], v[120:123], v[66:69]
	v_mfma_f32_16x16x32_bf16 v[6:9], v[6:9], v[120:123], v[70:73]
	v_mfma_f32_16x16x32_bf16 v[10:13], v[10:13], v[120:123], v[74:77]
	v_mfma_f32_16x16x32_bf16 v[14:17], v[14:17], v[120:123], v[78:81]
	ds_read_b128 v[66:69], v83
	ds_read_b128 v[70:73], v83 offset:2048
	ds_read_b128 v[74:77], v83 offset:4096
	ds_read_b128 v[78:81], v83 offset:6144
	ds_read_b128 v[120:123], v0 offset:16384
	s_waitcnt lgkmcnt(0)
	v_mfma_f32_16x16x32_bf16 v[22:25], v[66:69], v[120:123], v[22:25]
	v_mfma_f32_16x16x32_bf16 v[26:29], v[70:73], v[120:123], v[26:29]
	v_mfma_f32_16x16x32_bf16 v[30:33], v[74:77], v[120:123], v[30:33]
	v_mfma_f32_16x16x32_bf16 v[18:21], v[78:81], v[120:123], v[18:21]
	ds_read_b128 v[120:123], v0 offset:18432
	s_waitcnt lgkmcnt(0)
	v_mfma_f32_16x16x32_bf16 v[92:95], v[66:69], v[120:123], v[92:95]
	v_mfma_f32_16x16x32_bf16 v[96:99], v[70:73], v[120:123], v[96:99]
	v_mfma_f32_16x16x32_bf16 v[100:103], v[74:77], v[120:123], v[100:103]
	v_mfma_f32_16x16x32_bf16 v[88:91], v[78:81], v[120:123], v[88:91]
	ds_read_b128 v[120:123], v0 offset:20480
	s_waitcnt lgkmcnt(0)
	v_mfma_f32_16x16x32_bf16 v[108:111], v[66:69], v[120:123], v[108:111]
	v_mfma_f32_16x16x32_bf16 v[112:115], v[70:73], v[120:123], v[112:115]
	v_mfma_f32_16x16x32_bf16 v[116:119], v[74:77], v[120:123], v[116:119]
	v_mfma_f32_16x16x32_bf16 v[104:107], v[78:81], v[120:123], v[104:107]
	ds_read_b128 v[120:123], v0 offset:22528
	s_waitcnt lgkmcnt(0)
	v_mfma_f32_16x16x32_bf16 v[2:5], v[66:69], v[120:123], v[2:5]
	v_mfma_f32_16x16x32_bf16 v[6:9], v[70:73], v[120:123], v[6:9]
	v_mfma_f32_16x16x32_bf16 v[10:13], v[74:77], v[120:123], v[10:13]
	v_mfma_f32_16x16x32_bf16 v[14:17], v[78:81], v[120:123], v[14:17]
	s_setprio 0
	s_waitcnt vmcnt(7)
	ds_write_b128 v85, v[34:37] offset:32768
	s_waitcnt vmcnt(6)
	ds_write_b128 v85, v[38:41] offset:49152
	s_waitcnt vmcnt(5)
	ds_write_b128 v85, v[42:45] offset:36864
	s_waitcnt vmcnt(4)
	ds_write_b128 v85, v[46:49] offset:53248
	s_waitcnt vmcnt(3)
	ds_write_b128 v85, v[50:53] offset:40960
	s_waitcnt vmcnt(2)
	ds_write_b128 v85, v[54:57] offset:57344
	s_waitcnt vmcnt(1)
	ds_write_b128 v85, v[58:61] offset:45056
	s_waitcnt vmcnt(0)
	ds_write_b128 v85, v[62:65] offset:61440
	s_waitcnt lgkmcnt(0)
	s_barrier
	s_setprio 1
	ds_read_b128 v[34:37], v86 offset:32768
	ds_read_b128 v[38:41], v86 offset:34816
	ds_read_b128 v[42:45], v86 offset:36864
	ds_read_b128 v[46:49], v86 offset:38912
	ds_read_b128 v[50:53], v84 offset:49152
	s_waitcnt lgkmcnt(0)
	v_mfma_f32_16x16x32_bf16 v[22:25], v[34:37], v[50:53], v[22:25]
	ds_read_b128 v[66:69], v84 offset:53248
	v_mfma_f32_16x16x32_bf16 v[26:29], v[38:41], v[50:53], v[26:29]
	v_mfma_f32_16x16x32_bf16 v[30:33], v[42:45], v[50:53], v[30:33]
	v_mfma_f32_16x16x32_bf16 v[18:21], v[46:49], v[50:53], v[18:21]
	ds_read_b128 v[50:53], v84 offset:51200
	ds_read_b128 v[84:87], v84 offset:55296
	s_waitcnt lgkmcnt(1)
	v_mfma_f32_16x16x32_bf16 v[54:57], v[34:37], v[50:53], v[92:95]
	v_mfma_f32_16x16x32_bf16 v[58:61], v[38:41], v[50:53], v[96:99]
	v_mfma_f32_16x16x32_bf16 v[62:65], v[42:45], v[50:53], v[100:103]
	v_mfma_f32_16x16x32_bf16 v[50:53], v[46:49], v[50:53], v[88:91]
	v_mfma_f32_16x16x32_bf16 v[70:73], v[34:37], v[66:69], v[108:111]
	v_mfma_f32_16x16x32_bf16 v[74:77], v[38:41], v[66:69], v[112:115]
	v_mfma_f32_16x16x32_bf16 v[78:81], v[42:45], v[66:69], v[116:119]
	v_mfma_f32_16x16x32_bf16 v[66:69], v[46:49], v[66:69], v[104:107]
	s_waitcnt lgkmcnt(0)
	v_mfma_f32_16x16x32_bf16 v[2:5], v[34:37], v[84:87], v[2:5]
	v_mfma_f32_16x16x32_bf16 v[6:9], v[38:41], v[84:87], v[6:9]
	v_mfma_f32_16x16x32_bf16 v[10:13], v[42:45], v[84:87], v[10:13]
	v_mfma_f32_16x16x32_bf16 v[14:17], v[46:49], v[84:87], v[14:17]
	ds_read_b128 v[34:37], v83 offset:32768
	ds_read_b128 v[38:41], v83 offset:34816
	ds_read_b128 v[42:45], v83 offset:36864
	ds_read_b128 v[46:49], v83 offset:38912
	ds_read_b128 v[84:87], v0 offset:49152
	s_waitcnt lgkmcnt(0)
	v_mfma_f32_16x16x32_bf16 v[22:25], v[34:37], v[84:87], v[22:25]
	v_mfma_f32_16x16x32_bf16 v[26:29], v[38:41], v[84:87], v[26:29]
	v_mfma_f32_16x16x32_bf16 v[30:33], v[42:45], v[84:87], v[30:33]
	v_mfma_f32_16x16x32_bf16 v[18:21], v[46:49], v[84:87], v[18:21]
	ds_read_b128 v[84:87], v0 offset:51200
	s_waitcnt lgkmcnt(0)
	v_mfma_f32_16x16x32_bf16 v[54:57], v[34:37], v[84:87], v[54:57]
	v_mfma_f32_16x16x32_bf16 v[58:61], v[38:41], v[84:87], v[58:61]
	v_mfma_f32_16x16x32_bf16 v[62:65], v[42:45], v[84:87], v[62:65]
	v_mfma_f32_16x16x32_bf16 v[50:53], v[46:49], v[84:87], v[50:53]
	ds_read_b128 v[84:87], v0 offset:53248
	s_waitcnt lgkmcnt(0)
	v_mfma_f32_16x16x32_bf16 v[70:73], v[34:37], v[84:87], v[70:73]
	v_mfma_f32_16x16x32_bf16 v[74:77], v[38:41], v[84:87], v[74:77]
	v_mfma_f32_16x16x32_bf16 v[78:81], v[42:45], v[84:87], v[78:81]
	v_mfma_f32_16x16x32_bf16 v[66:69], v[46:49], v[84:87], v[66:69]
	ds_read_b128 v[84:87], v0 offset:55296
	s_waitcnt lgkmcnt(0)
	v_mfma_f32_16x16x32_bf16 v[2:5], v[34:37], v[84:87], v[2:5]
	v_mfma_f32_16x16x32_bf16 v[6:9], v[38:41], v[84:87], v[6:9]
	v_mfma_f32_16x16x32_bf16 v[10:13], v[42:45], v[84:87], v[10:13]
	v_mfma_f32_16x16x32_bf16 v[14:17], v[46:49], v[84:87], v[14:17]
	s_setprio 0
	v_mov_b32_e32 v0, v169
	s_barrier
; DI int tidx() { int t = threadIdx.x & 255; asm volatile("" : "+v"(t)); return t; }
; DI void stage_c(const f32x4 (&acc)[4][4], float* Cs) {
;   const int tid = tidx(), lane = tid & 63, w = tid >> 6;
;   const int wm = w >> 1, wn = w & 1, fr = lane & 15, fq = lane >> 4;
; #pragma unroll
;   for (int m = 0; m < 4; ++m)
; #pragma unroll
;     for (int n = 0; n < 4; ++n)
; #pragma unroll
;       for (int j = 0; j < 4; ++j) Cs[(wm * 64 + m * 16 + fq * 4 + j) * CST + wn * 64 + n * 16 + fr] = acc[m][n][j];
;   __syncthreads();
; DI void q_tile(PREF p, int l, int idx, unsigned char* ldsb) {
;     ...
;   for (int q = 0; q < 8; ++q) {
;     int r = (tid >> 4) + 16 * q, c = (tid & 15) * 8;
;     int n = col0 + c; int dd = n % 96;
;     float rs = aux[r];
;     float v[8]; ld8(Cs + r * CST + c, v);
; #pragma unroll
;     for (int j = 0; j < 8; ++j) v[j] *= rs;
;     if (dd >= 64) {
;       int ri0 = dd - 64; int s = (row0 + r) & 4095;
;       float pv[8];
;       if (ri0 < 16) {
;         ld8(Cs + r * CST + c + 16, pv);
;         const float* cs = p.rcos + s * 16 + ri0; const float* sn = p.rsin + s * 16 + ri0;
; #pragma unroll
;         for (int j = 0; j < 8; ++j) v[j] = v[j] * cs[j] - pv[j] * rs * sn[j];
;       } else {
;         ld8(Cs + r * CST + c - 16, pv);
;         const float* cs = p.rcos + s * 16 + ri0 - 16; const float* sn = p.rsin + s * 16 + ri0 - 16;
	s_mov_b32 s0, 0xfffffc0
	v_lshrrev_b32_e32 v35, 2, v0
	v_lshrrev_b32_e32 v34, 1, v0
	v_and_b32_e32 v35, 12, v35
	v_and_or_b32 v34, v34, s0, v35
	v_and_b32_e32 v0, 0x4f, v0
	v_mul_lo_u32 v34, v34, s92
	v_lshlrev_b32_e32 v0, 2, v0
	v_add3_u32 v0, s33, v34, v0
	ds_write2_b32 v0, v22, v54 offset1:16
	ds_write2_b32 v0, v23, v55 offset0:132 offset1:148
	v_add_u32_e32 v22, 0x400, v0
	ds_write2_b32 v22, v24, v56 offset0:8 offset1:24
	ds_write2_b32 v22, v25, v57 offset0:140 offset1:156
	ds_write2_b32 v0, v70, v2 offset0:32 offset1:48
	ds_write2_b32 v0, v71, v3 offset0:164 offset1:180
	ds_write2_b32 v22, v72, v4 offset0:40 offset1:56
	ds_write2_b32 v22, v73, v5 offset0:172 offset1:188
	v_add_u32_e32 v2, 0x2000, v0
	v_add_u32_e32 v3, 0x2400, v0
	ds_write2_b32 v2, v26, v58 offset0:64 offset1:80
	ds_write2_b32 v2, v27, v59 offset0:196 offset1:212
	ds_write2_b32 v3, v28, v60 offset0:72 offset1:88
	ds_write2_b32 v3, v29, v61 offset0:204 offset1:220
	ds_write2_b32 v2, v74, v6 offset0:96 offset1:112
	ds_write2_b32 v2, v75, v7 offset0:228 offset1:244
	ds_write2_b32 v3, v76, v8 offset0:104 offset1:120
	ds_write2_b32 v3, v77, v9 offset0:236 offset1:252
	v_add_u32_e32 v2, 0x4000, v0
	v_add_u32_e32 v3, 0x4400, v0
	v_add_u32_e32 v4, 0x4800, v0
	ds_write2_b32 v2, v30, v62 offset0:128 offset1:144
	ds_write2_b32 v3, v31, v63 offset0:4 offset1:20
	ds_write2_b32 v3, v32, v64 offset0:136 offset1:152
	ds_write2_b32 v4, v33, v65 offset0:12 offset1:28
	ds_write2_b32 v2, v78, v10 offset0:160 offset1:176
	ds_write2_b32 v3, v79, v11 offset0:36 offset1:52
	ds_write2_b32 v3, v80, v12 offset0:168 offset1:184
	ds_write2_b32 v4, v81, v13 offset0:44 offset1:60
	v_add_u32_e32 v2, 0x6000, v0
	v_add_u32_e32 v3, 0x6400, v0
	v_add_u32_e32 v0, 0x6800, v0
	ds_write2_b32 v2, v18, v50 offset0:192 offset1:208
	ds_write2_b32 v3, v19, v51 offset0:68 offset1:84
	ds_write2_b32 v3, v20, v52 offset0:200 offset1:216
	ds_write2_b32 v0, v21, v53 offset0:76 offset1:92
	ds_write2_b32 v2, v66, v14 offset0:224 offset1:240
	ds_write2_b32 v3, v67, v15 offset0:100 offset1:116
	ds_write2_b32 v3, v68, v16 offset0:232 offset1:248
	ds_write2_b32 v0, v69, v17 offset0:108 offset1:124
	v_lshlrev_b32_e32 v0, 3, v82
	v_and_b32_e32 v0, 0x78, v0
	v_or_b32_e32 v6, s8, v0
	s_mov_b32 s0, 0x2aaaaaab
	v_mul_hi_i32 v2, v6, s0
	v_lshrrev_b32_e32 v3, 31, v2
	v_lshrrev_b32_e32 v2, 4, v2
	v_add_u32_e32 v2, v2, v3
	s_movk_i32 s0, 0x60
	v_mul_lo_u32 v2, v2, s0
	v_ashrrev_i32_e32 v17, 4, v82
	v_sub_u32_e32 v2, v6, v2
	s_movk_i32 s0, 0x4f
	v_lshl_add_u32 v22, v0, 2, s33
	v_cmp_lt_u32_e32 vcc, s0, v2
	v_readlane_b32 s0, v254, 16
	v_mul_lo_u32 v23, v17, s92
	v_add_u32_e32 v7, v22, v23
	v_lshl_add_u32 v21, v17, 2, s0
	v_mov_b32_e32 v80, 0xffffffc0
	v_subrev_u32_e32 v132, 64, v2
	v_lshlrev_b32_e32 v132, 2, v132
	v_cndmask_b32_e32 v80, v1, v80, vcc
	v_add_u32_e32 v132, v132, v80
	v_ashrrev_i32_e32 v133, 31, v132
	v_lshl_add_u64 v[134:135], s[12:13], 0, v[132:133]
	v_lshl_add_u64 v[136:137], s[14:15], 0, v[132:133]
	v_add_u32_e32 v138, s18, v17
	v_mov_b32_e32 v141, 0
	v_and_b32_e32 v140, 0xfff, v138
	v_lshlrev_b32_e32 v140, 6, v140
	v_lshl_add_u64 v[142:143], v[134:135], 0, v[140:141]
	global_load_dwordx4 v[96:99], v[142:143], off
	global_load_dwordx4 v[100:103], v[142:143], off offset:16
	v_lshl_add_u64 v[142:143], v[136:137], 0, v[140:141]
	global_load_dwordx4 v[104:107], v[142:143], off
	global_load_dwordx4 v[108:111], v[142:143], off offset:16
	v_add_u32_e32 v140, 16, v138
	v_and_b32_e32 v140, 0xfff, v140
	v_lshlrev_b32_e32 v140, 6, v140
	v_lshl_add_u64 v[142:143], v[134:135], 0, v[140:141]
	global_load_dwordx4 v[112:115], v[142:143], off
	global_load_dwordx4 v[120:123], v[142:143], off offset:16
	v_lshl_add_u64 v[142:143], v[136:137], 0, v[140:141]
	global_load_dwordx4 v[124:127], v[142:143], off
	global_load_dwordx4 v[128:131], v[142:143], off offset:16
	v_add_u32_e32 v140, 32, v138
	v_and_b32_e32 v140, 0xfff, v140
	v_lshlrev_b32_e32 v140, 6, v140
	v_lshl_add_u64 v[142:143], v[134:135], 0, v[140:141]
	global_load_dwordx4 v[96:99], v[142:143], off
	global_load_dwordx4 v[100:103], v[142:143], off offset:16
	v_lshl_add_u64 v[142:143], v[136:137], 0, v[140:141]
	global_load_dwordx4 v[104:107], v[142:143], off
	global_load_dwordx4 v[108:111], v[142:143], off offset:16
	v_add_u32_e32 v140, 48, v138
	v_and_b32_e32 v140, 0xfff, v140
	v_lshlrev_b32_e32 v140, 6, v140
	v_lshl_add_u64 v[142:143], v[134:135], 0, v[140:141]
	global_load_dwordx4 v[112:115], v[142:143], off
	global_load_dwordx4 v[120:123], v[142:143], off offset:16
	v_lshl_add_u64 v[142:143], v[136:137], 0, v[140:141]
	global_load_dwordx4 v[124:127], v[142:143], off
	global_load_dwordx4 v[128:131], v[142:143], off offset:16
	v_add_u32_e32 v140, 64, v138
	v_and_b32_e32 v140, 0xfff, v140
	v_lshlrev_b32_e32 v140, 6, v140
	v_lshl_add_u64 v[142:143], v[134:135], 0, v[140:141]
	global_load_dwordx4 v[96:99], v[142:143], off
	global_load_dwordx4 v[100:103], v[142:143], off offset:16
	v_lshl_add_u64 v[142:143], v[136:137], 0, v[140:141]
	global_load_dwordx4 v[104:107], v[142:143], off
	global_load_dwordx4 v[108:111], v[142:143], off offset:16
	v_add_u32_e32 v140, 80, v138
	v_and_b32_e32 v140, 0xfff, v140
	v_lshlrev_b32_e32 v140, 6, v140
	v_lshl_add_u64 v[142:143], v[134:135], 0, v[140:141]
	global_load_dwordx4 v[112:115], v[142:143], off
	global_load_dwordx4 v[120:123], v[142:143], off offset:16
	v_lshl_add_u64 v[142:143], v[136:137], 0, v[140:141]
	global_load_dwordx4 v[124:127], v[142:143], off
	global_load_dwordx4 v[128:131], v[142:143], off offset:16
	v_add_u32_e32 v140, 96, v138
	v_and_b32_e32 v140, 0xfff, v140
	v_lshlrev_b32_e32 v140, 6, v140
	v_lshl_add_u64 v[142:143], v[134:135], 0, v[140:141]
	global_load_dwordx4 v[96:99], v[142:143], off
	global_load_dwordx4 v[100:103], v[142:143], off offset:16
	v_lshl_add_u64 v[142:143], v[136:137], 0, v[140:141]
	global_load_dwordx4 v[104:107], v[142:143], off
	global_load_dwordx4 v[108:111], v[142:143], off offset:16
	v_add_u32_e32 v140, 112, v138
	v_and_b32_e32 v140, 0xfff, v140
	v_lshlrev_b32_e32 v140, 6, v140
	v_lshl_add_u64 v[142:143], v[134:135], 0, v[140:141]
	global_load_dwordx4 v[112:115], v[142:143], off
	global_load_dwordx4 v[120:123], v[142:143], off offset:16
	v_lshl_add_u64 v[142:143], v[136:137], 0, v[140:141]
	global_load_dwordx4 v[124:127], v[142:143], off
	global_load_dwordx4 v[128:131], v[142:143], off offset:16
	s_waitcnt lgkmcnt(0)
	s_barrier
; DI void q_tile(PREF p, int l, int idx, unsigned char* ldsb) {
;     ...
;     int r = (tid >> 4) + 16 * q, c = (tid & 15) * 8;
;     int n = col0 + c; int dd = n % 96;
;     float rs = aux[r];
;     float v[8]; ld8(Cs + r * CST + c, v);
; #pragma unroll
;     for (int j = 0; j < 8; ++j) v[j] *= rs;
;     if (dd >= 64) {
;       int ri0 = dd - 64; int s = (row0 + r) & 4095;
;       float pv[8];
;       if (ri0 < 16) {
;         ld8(Cs + r * CST + c + 16, pv);
;         const float* cs = p.rcos + s * 16 + ri0; const float* sn = p.rsin + s * 16 + ri0;
; #pragma unroll
;         for (int j = 0; j < 8; ++j) v[j] = v[j] * cs[j] - pv[j] * rs * sn[j];
;       } else {
;         ld8(Cs + r * CST + c - 16, pv);
;         const float* cs = p.rcos + s * 16 + ri0 - 16; const float* sn = p.rsin + s * 16 + ri0 - 16;
; #pragma unroll
;         for (int j = 0; j < 8; ++j) v[j] = v[j] * cs[j] + pv[j] * rs * sn[j];
;       }
	ds_read_b32 v16, v21
	ds_read_b128 v[8:11], v7
	ds_read_b128 v[24:27], v7 offset:16
	v_subrev_u32_e32 v0, 64, v2
	v_cmp_lt_i32_e64 s[8:9], 63, v2
	v_lshlrev_b64 v[2:3], 2, v[0:1]
	v_lshl_add_u64 v[4:5], s[12:13], 0, v[2:3]
	v_lshl_add_u64 v[2:3], s[14:15], 0, v[2:3]
	s_waitcnt lgkmcnt(1)
	v_pk_mul_f32 v[14:15], v[16:17], v[8:9] op_sel_hi:[0,1]
	v_pk_mul_f32 v[12:13], v[16:17], v[10:11] op_sel_hi:[0,1]
	s_waitcnt lgkmcnt(0)
	v_pk_mul_f32 v[10:11], v[16:17], v[24:25] op_sel_hi:[0,1]
	v_pk_mul_f32 v[8:9], v[16:17], v[26:27] op_sel_hi:[0,1]
	v_add_u32_e32 v20, s18, v17
	s_and_saveexec_b64 s[16:17], s[8:9]
	s_cbranch_execz .LBB0_354
	v_lshlrev_b32_e32 v0, 4, v20
	v_and_b32_e32 v0, 0xfff0, v0
	v_lshlrev_b32_e32 v0, 2, v0
	v_mov_b32_e32 v17, v16
	v_lshl_add_u64 v[18:19], v[4:5], 0, v[0:1]
	s_and_saveexec_b64 s[0:1], vcc
	s_xor_b64 s[18:19], exec, s[0:1]
	s_cbranch_execz .LBB0_351
	v_subrev_u32_e32 v24, 64, v7
	v_lshl_add_u64 v[40:41], v[2:3], 0, v[0:1]
	ds_read_b128 v[24:27], v24
	global_load_dwordx4 v[28:31], v[18:19], off offset:-48
	global_load_dwordx4 v[32:35], v[18:19], off offset:-64
	global_load_dwordx4 v[36:39], v[40:41], off offset:-48
	s_nop 0
	global_load_dwordx4 v[40:43], v[40:41], off offset:-64
	v_subrev_u32_e32 v7, 48, v7
	s_waitcnt lgkmcnt(0)
	v_pk_mul_f32 v[18:19], v[16:17], v[24:25]
	s_waitcnt vmcnt(0)
	v_pk_mul_f32 v[18:19], v[18:19], v[40:41]
	s_nop 0
	v_pk_fma_f32 v[14:15], v[14:15], v[32:33], v[18:19]
	v_pk_mul_f32 v[18:19], v[16:17], v[26:27]
	ds_read_b128 v[24:27], v7
	v_pk_mul_f32 v[18:19], v[18:19], v[42:43]
	s_nop 0
	v_pk_fma_f32 v[12:13], v[12:13], v[34:35], v[18:19]
	s_waitcnt lgkmcnt(0)
	v_pk_mul_f32 v[18:19], v[16:17], v[24:25]
	v_pk_mul_f32 v[16:17], v[16:17], v[26:27]
	v_pk_mul_f32 v[18:19], v[18:19], v[36:37]
	v_pk_mul_f32 v[16:17], v[16:17], v[38:39]
	v_pk_fma_f32 v[10:11], v[10:11], v[28:29], v[18:19]
	v_pk_fma_f32 v[8:9], v[8:9], v[30:31], v[16:17]
